# N2: final-norm weight quads loaded once before the row loop (were re-loaded per row behind each store)
# speedup vs baseline: 1.0079x; 1.0073x over previous
.LBB0_423:
	s_and_b64 vcc, exec, s[2:3]
	s_cbranch_vccz .LBB0_430
	s_waitcnt vmcnt(0)
	v_mbcnt_lo_u32_b32 v1, -1, 0
	v_mbcnt_hi_u32_b32 v1, -1, v1
	s_mov_b32 s6, s0
	v_add_u32_e32 v0, s87, v1
	v_ashrrev_i32_e32 v0, 6, v0
	v_readlane_b32 s0, v254, 24
	v_readlane_b32 s1, v254, 25
	s_nop 0
	v_add_u32_e32 v22, s0, v0
	s_movk_i32 s0, 0x3000
	v_cmp_gt_i32_e32 vcc, s0, v22
	s_and_saveexec_b64 s[2:3], vcc
	s_movk_i32 s7, 0x2fff
	s_cbranch_execz .LBB0_427
	v_lshlrev_b32_e32 v2, 2, v1
	v_and_b32_e32 v3, 0xfc, v2
	s_movk_i32 s0, 0x80
	v_lshlrev_b32_e32 v128, 2, v3
	v_bitop3_b32 v23, v2, s0, v242 bitop3:0x6c
	v_bitop3_b32 v24, v2, 64, v242 bitop3:0x6c
	v_bitop3_b32 v25, v2, 32, v242 bitop3:0x6c
	v_bitop3_b32 v26, v2, 16, v242 bitop3:0x6c
	v_bitop3_b32 v27, v2, 8, v242 bitop3:0x6c
	v_bitop3_b32 v28, v2, 4, v242 bitop3:0x6c
	v_or_b32_e32 v2, 0x1000, v128
	v_mov_b32_e32 v3, v129
	v_lshl_add_u64 v[10:11], s[76:77], 0, v[2:3]
	v_or_b32_e32 v2, 0x1400, v128
	v_lshl_add_u64 v[8:9], s[76:77], 0, v[128:129]
	v_lshl_add_u64 v[12:13], s[76:77], 0, v[2:3]
	v_or_b32_e32 v2, 0x1800, v128
	v_or_b32_e32 v128, 0x1c00, v128
	v_and_b32_e32 v1, 63, v1
	v_readlane_b32 s0, v254, 24
	v_lshl_add_u64 v[16:17], s[76:77], 0, v[128:129]
	v_lshlrev_b32_e32 v128, 4, v1
	v_ashrrev_i32_e32 v1, 31, v0
	v_readlane_b32 s1, v254, 25
	v_lshl_add_u64 v[14:15], s[76:77], 0, v[2:3]
	s_mov_b64 s[4:5], 0
	v_lshl_add_u64 v[0:1], s[0:1], 0, v[0:1]
	v_lshlrev_b64 v[0:1], 13, v[0:1]
	v_lshl_add_u64 v[18:19], s[80:81], 0, v[0:1]
	v_lshl_add_u64 v[20:21], s[78:79], 0, v[0:1]
	global_load_dwordx4 v[54:57], v[8:9], off
	global_load_dwordx4 v[80:83], v[8:9], off offset:1024
	global_load_dwordx4 v[84:87], v[8:9], off offset:2048
	global_load_dwordx4 v[88:91], v[8:9], off offset:3072
	global_load_dwordx4 v[92:95], v[10:11], off
	global_load_dwordx4 v[96:99], v[12:13], off
	global_load_dwordx4 v[100:103], v[14:15], off
	global_load_dwordx4 v[104:107], v[16:17], off
.LBB0_426:
	v_lshl_add_u64 v[30:31], v[18:19], 0, v[128:129]
	s_mov_b32 s0, 0x4279000
	v_add_co_u32_e64 v50, s[38:39], s0, v30
	v_add_co_u32_e32 v46, vcc, 0x4278000, v30
	s_nop 0
	v_addc_co_u32_e64 v51, s[38:39], 0, v31, s[38:39]
	global_load_dwordx4 v[4:7], v[50:51], off
	global_load_dwordx4 v[0:3], v[50:51], off offset:1024
	v_addc_co_u32_e32 v47, vcc, 0, v31, vcc
	global_load_dwordx4 v[30:33], v[50:51], off offset:2048
	global_load_dwordx4 v[34:37], v[46:47], off
	global_load_dwordx4 v[38:41], v[46:47], off offset:1024
	global_load_dwordx4 v[42:45], v[46:47], off offset:2048
	s_nop 0
	global_load_dwordx4 v[46:49], v[46:47], off offset:3072
	s_nop 0
	global_load_dwordx4 v[50:53], v[50:51], off offset:3072
	s_nop 0
	v_lshl_add_u64 v[58:59], v[20:21], 0, v[128:129]
	v_add_u32_e32 v22, s6, v22
	v_lshl_add_u64 v[18:19], v[18:19], 0, s[18:19]
	v_lshl_add_u64 v[20:21], v[20:21], 0, s[18:19]
	s_waitcnt vmcnt(0)
	v_mov_b32_e32 v70, v31
	v_mul_f32_e32 v29, v35, v35
	v_mul_f32_e32 v76, v39, v39
	v_mul_f32_e32 v77, v43, v43
	v_fmac_f32_e32 v29, v34, v34
	v_fmac_f32_e32 v76, v38, v38
	v_mov_b32_e32 v62, v5
	v_mov_b32_e32 v63, v1
	v_mul_f32_e32 v78, v47, v47
	v_fmac_f32_e32 v77, v42, v42
	v_fmac_f32_e32 v29, v36, v36
	v_fmac_f32_e32 v76, v40, v40
	v_mov_b32_e32 v60, v4
	v_mov_b32_e32 v61, v0
	v_pk_mul_f32 v[62:63], v[62:63], v[62:63]
	v_fmac_f32_e32 v78, v46, v46
	v_fmac_f32_e32 v77, v44, v44
	v_fmac_f32_e32 v29, v37, v37
	v_fmac_f32_e32 v76, v41, v41
	v_mov_b32_e32 v64, v6
	v_mov_b32_e32 v65, v2
	v_mov_b32_e32 v71, v51
	v_pk_fma_f32 v[60:61], v[60:61], v[60:61], v[62:63]
	v_fmac_f32_e32 v78, v48, v48
	v_fmac_f32_e32 v77, v45, v45
	v_add_f32_e32 v29, v29, v76
	v_mov_b32_e32 v66, v7
	v_mov_b32_e32 v67, v3
	v_mov_b32_e32 v68, v30
	v_mov_b32_e32 v69, v50
	v_pk_mul_f32 v[70:71], v[70:71], v[70:71]
	v_pk_fma_f32 v[60:61], v[64:65], v[64:65], v[60:61]
	v_fmac_f32_e32 v78, v49, v49
	v_add_f32_e32 v29, v29, v77
	v_mov_b32_e32 v72, v32
	v_mov_b32_e32 v73, v52
	v_pk_fma_f32 v[62:63], v[68:69], v[68:69], v[70:71]
	v_pk_fma_f32 v[60:61], v[66:67], v[66:67], v[60:61]
	v_add_f32_e32 v29, v29, v78
	v_mov_b32_e32 v74, v33
	v_mov_b32_e32 v75, v53
	v_pk_fma_f32 v[62:63], v[72:73], v[72:73], v[62:63]
	v_add_f32_e32 v29, v29, v60
	v_pk_fma_f32 v[62:63], v[74:75], v[74:75], v[62:63]
	v_add_f32_e32 v29, v29, v61
	v_add_f32_e32 v29, v29, v62
	v_add_f32_e32 v29, v29, v63
	ds_bpermute_b32 v60, v23, v29
	s_waitcnt lgkmcnt(0)
	v_add_f32_e32 v29, v29, v60
	ds_bpermute_b32 v60, v24, v29
	s_waitcnt lgkmcnt(0)
	v_add_f32_e32 v29, v29, v60
	ds_bpermute_b32 v60, v25, v29
	s_waitcnt lgkmcnt(0)
	v_add_f32_e32 v29, v29, v60
	ds_bpermute_b32 v60, v26, v29
	s_waitcnt lgkmcnt(0)
	v_add_f32_e32 v29, v29, v60
	ds_bpermute_b32 v60, v27, v29
	s_waitcnt lgkmcnt(0)
	v_add_f32_e32 v29, v29, v60
	ds_bpermute_b32 v60, v28, v29
	s_waitcnt lgkmcnt(0)
	v_add_f32_e32 v29, v29, v60
	v_fmamk_f32 v29, v29, 0x3a000000, v234
	v_mul_f32_e32 v60, 0x4b800000, v29
	v_cmp_gt_f32_e32 vcc, s25, v29
	s_nop 1
	v_cndmask_b32_e32 v29, v29, v60, vcc
	v_rsq_f32_e32 v29, v29
	s_nop 0
	v_mul_f32_e32 v60, 0x45800000, v29
	v_cndmask_b32_e32 v60, v29, v60, vcc
	v_pk_mul_f32 v[34:35], v[34:35], v[60:61] op_sel_hi:[1,0]
	v_pk_mul_f32 v[36:37], v[36:37], v[60:61] op_sel_hi:[1,0]
	v_pk_mul_f32 v[34:35], v[54:55], v[34:35]
	v_pk_mul_f32 v[36:37], v[56:57], v[36:37]
	global_store_dwordx4 v[58:59], v[34:37], off
	v_pk_mul_f32 v[40:41], v[40:41], v[60:61] op_sel_hi:[1,0]
	v_pk_mul_f32 v[38:39], v[38:39], v[60:61] op_sel_hi:[1,0]
	v_pk_mul_f32 v[6:7], v[6:7], v[60:61] op_sel_hi:[1,0]
	v_pk_mul_f32 v[4:5], v[4:5], v[60:61] op_sel_hi:[1,0]
	v_pk_mul_f32 v[2:3], v[2:3], v[60:61] op_sel_hi:[1,0]
	v_pk_mul_f32 v[0:1], v[0:1], v[60:61] op_sel_hi:[1,0]
	v_pk_mul_f32 v[34:35], v[80:81], v[38:39]
	v_pk_mul_f32 v[36:37], v[82:83], v[40:41]
	global_store_dwordx4 v[58:59], v[34:37], off offset:1024
	s_nop 0
	v_pk_mul_f32 v[38:39], v[44:45], v[60:61] op_sel_hi:[1,0]
	v_pk_mul_f32 v[40:41], v[42:43], v[60:61] op_sel_hi:[1,0]
	v_pk_mul_f32 v[36:37], v[86:87], v[38:39]
	v_pk_mul_f32 v[34:35], v[84:85], v[40:41]
	global_store_dwordx4 v[58:59], v[34:37], off offset:2048
	s_nop 0
	v_pk_mul_f32 v[38:39], v[48:49], v[60:61] op_sel_hi:[1,0]
	v_pk_mul_f32 v[40:41], v[46:47], v[60:61] op_sel_hi:[1,0]
	v_pk_mul_f32 v[36:37], v[90:91], v[38:39]
	v_pk_mul_f32 v[34:35], v[88:89], v[40:41]
	global_store_dwordx4 v[58:59], v[34:37], off offset:3072
	v_add_co_u32_e32 v38, vcc, s85, v58
	v_pk_mul_f32 v[4:5], v[92:93], v[4:5]
	v_addc_co_u32_e32 v39, vcc, 0, v59, vcc
	v_pk_mul_f32 v[6:7], v[94:95], v[6:7]
	global_store_dwordx4 v[38:39], v[4:7], off
	v_cmp_lt_i32_e32 vcc, s7, v22
	s_or_b64 s[4:5], vcc, s[4:5]
	v_pk_mul_f32 v[0:1], v[96:97], v[0:1]
	v_pk_mul_f32 v[2:3], v[98:99], v[2:3]
	global_store_dwordx4 v[38:39], v[0:3], off offset:1024
	s_nop 0
	v_pk_mul_f32 v[4:5], v[32:33], v[60:61] op_sel_hi:[1,0]
	v_pk_mul_f32 v[6:7], v[30:31], v[60:61] op_sel_hi:[1,0]
	v_pk_mul_f32 v[2:3], v[102:103], v[4:5]
	v_pk_mul_f32 v[0:1], v[100:101], v[6:7]
	global_store_dwordx4 v[38:39], v[0:3], off offset:2048
	s_nop 0
	v_pk_mul_f32 v[4:5], v[52:53], v[60:61] op_sel_hi:[1,0]
	v_pk_mul_f32 v[6:7], v[50:51], v[60:61] op_sel_hi:[1,0]
	v_pk_mul_f32 v[2:3], v[106:107], v[4:5]
	v_pk_mul_f32 v[0:1], v[104:105], v[6:7]
	global_store_dwordx4 v[38:39], v[0:3], off offset:3072
	s_andn2_b64 exec, exec, s[4:5]
	s_cbranch_execnz .LBB0_426
